# phase-2 item classes staggered four ways over workgroups (was two ways) to smooth the memory-bound sample items
# baseline (speedup 1.0000x reference)
.LBB0_682:
	s_and_b32 s2, s47, 3
	s_lshl_b32 s2, s2, 9
	s_add_i32 s2, s33, s2
	s_and_b32 s4, s2, 0x7ff
	s_cmpk_eq_i32 s46, 0x100
	s_cselect_b32 s56, s4, s33
	s_cmpk_gt_i32 s56, 0x2ff
	s_mov_b64 s[2:3], -1
	s_cbranch_scc0 .LBB0_734
	s_cmpk_gt_u32 s56, 0x4ff
	s_cbranch_scc0 .LBB0_731
	s_cmpk_gt_u32 s56, 0x57f
	s_cbranch_scc0 .LBB0_726
	s_cmpk_gt_u32 s56, 0x67f
	s_cbranch_scc0 .LBB0_709
	s_cmpk_lt_u32 s56, 0x780
	s_cbranch_scc1 .LBB0_696
	v_and_b32_e32 v18, 63, v208
	v_lshrrev_b32_e32 v19, 6, v208
	v_and_b32_e32 v20, 3, v19
	v_lshrrev_b32_e32 v21, 2, v19
	v_and_b32_e32 v22, 15, v18
	v_lshrrev_b32_e32 v23, 4, v18
	v_lshlrev_b32_e32 v176, 2, v18
	v_xor_b32_e32 v238, 64, v176
	v_xor_b32_e32 v239, 0x80, v176
	s_and_b32 s2, s56, 0x7c
	s_and_b32 s94, s56, 3
	v_readfirstlane_b32 s6, v21
	v_add_u32_e32 v230, s2, v20
	v_or_b32_e32 v230, 0x2000, v230
	v_mul_u32_u24_e32 v231, 0x5800, v230
	s_lshl_b32 s3, s94, 8
	v_lshl_add_u32 v232, v22, 4, v231
	v_add_u32_e32 v232, s3, v232
	v_add_u32_e32 v232, 0x5000, v232
	global_load_dwordx4 v[160:163], v232, s[0:1]
	v_add_u32_e32 v232, 0x400, v232
	v_mov_b32_e32 v233, 0
	v_lshl_add_u64 v[244:245], s[0:1], 0, v[232:233]
	v_mul_u32_u24_e32 v231, 0x1c00, v230
	v_lshl_add_u32 v232, v22, 4, v231
	v_add_u32_e32 v232, s3, v232
	v_add_u32_e32 v232, 0x1d301800, v232
	v_lshl_add_u64 v[246:247], s[96:97], 0, v[232:233]
	s_lshl_b32 s7, s2, 17
	s_lshl_b32 s8, s94, 9
	s_lshl_b32 s6, s6, 18
	s_add_u32 s7, s7, s8
	s_add_u32 s7, s7, s6
	s_add_u32 s2, s70, s7
	s_addc_u32 s3, s71, 0
	s_add_u32 s4, s72, s7
	s_addc_u32 s5, s73, 0
	v_lshlrev_b32_e32 v24, 15, v23
	v_lshl_add_u32 v24, v22, 5, v24
	v_add_u32_e32 v25, 0x1000, v24
	v_add_u32_e32 v26, 0x2000, v24
	v_add_u32_e32 v27, 0x3000, v24
	v_add_u32_e32 v28, 0x4000, v24
	v_add_u32_e32 v29, 0x5000, v24
	v_add_u32_e32 v30, 0x6000, v24
	v_add_u32_e32 v31, 0x7000, v24
	v_mov_b32_e32 v16, v206
	v_mov_b32_e32 v17, 0
	v_mov_b32_e32 v8, 0
	v_mov_b32_e32 v9, 0
	v_mov_b32_e32 v10, 0
	v_mov_b32_e32 v11, 0
	v_mov_b32_e32 v12, 0
	v_mov_b32_e32 v13, 0
	v_mov_b32_e32 v14, 0
	v_mov_b32_e32 v15, 0
	global_load_dwordx4 v[32:35], v24, s[2:3]
	global_load_dwordx4 v[36:39], v24, s[2:3] offset:16
	global_load_dwordx4 v[40:43], v24, s[2:3] offset:2048
	global_load_dwordx4 v[44:47], v24, s[2:3] offset:2064
	global_load_dwordx4 v[48:51], v25, s[2:3]
	global_load_dwordx4 v[52:55], v25, s[2:3] offset:16
	global_load_dwordx4 v[56:59], v25, s[2:3] offset:2048
	global_load_dwordx4 v[60:63], v25, s[2:3] offset:2064
	global_load_dwordx4 v[64:67], v26, s[2:3]
	global_load_dwordx4 v[68:71], v26, s[2:3] offset:16
	global_load_dwordx4 v[72:75], v26, s[2:3] offset:2048
	global_load_dwordx4 v[76:79], v26, s[2:3] offset:2064
	global_load_dwordx4 v[80:83], v27, s[2:3]
	global_load_dwordx4 v[84:87], v27, s[2:3] offset:16
	global_load_dwordx4 v[88:91], v27, s[2:3] offset:2048
	global_load_dwordx4 v[92:95], v27, s[2:3] offset:2064
	global_load_dwordx4 v[96:99], v28, s[2:3]
	global_load_dwordx4 v[100:103], v28, s[2:3] offset:16
	global_load_dwordx4 v[104:107], v28, s[2:3] offset:2048
	global_load_dwordx4 v[108:111], v28, s[2:3] offset:2064
	global_load_dwordx4 v[112:115], v29, s[2:3]
	global_load_dwordx4 v[116:119], v29, s[2:3] offset:16
	global_load_dwordx4 v[120:123], v29, s[2:3] offset:2048
	global_load_dwordx4 v[124:127], v29, s[2:3] offset:2064
	global_load_dwordx4 v[128:131], v30, s[2:3]
	global_load_dwordx4 v[132:135], v30, s[2:3] offset:16
	global_load_dwordx4 v[136:139], v30, s[2:3] offset:2048
	global_load_dwordx4 v[140:143], v30, s[2:3] offset:2064
	global_load_dwordx4 v[144:147], v31, s[2:3]
	global_load_dwordx4 v[148:151], v31, s[2:3] offset:16
	global_load_dwordx4 v[152:155], v31, s[2:3] offset:2048
	global_load_dwordx4 v[156:159], v31, s[2:3] offset:2064
	s_waitcnt vmcnt(32)
	v_lshlrev_b32_e32 v0, 16, v160
	v_and_b32_e32 v1, 0xffff0000, v160
	v_lshlrev_b32_e32 v2, 16, v161
	v_and_b32_e32 v3, 0xffff0000, v161
	v_lshlrev_b32_e32 v4, 16, v162
	v_and_b32_e32 v5, 0xffff0000, v162
	v_lshlrev_b32_e32 v6, 16, v163
	v_and_b32_e32 v7, 0xffff0000, v163
	s_waitcnt vmcnt(30)
	v_mul_f32_e32 v160, v32, v0
	v_fmac_f32_e32 v160, v33, v1
	v_fmac_f32_e32 v160, v34, v2
	v_fmac_f32_e32 v160, v35, v3
	v_fmac_f32_e32 v160, v36, v4
	v_fmac_f32_e32 v160, v37, v5
	v_fmac_f32_e32 v160, v38, v6
	v_fmac_f32_e32 v160, v39, v7
	global_load_dwordx4 v[32:35], v24, s[4:5]
	global_load_dwordx4 v[36:39], v24, s[4:5] offset:16
	s_waitcnt vmcnt(30)
	v_mul_f32_e32 v161, v40, v0
	v_fmac_f32_e32 v161, v41, v1
	v_fmac_f32_e32 v161, v42, v2
	v_fmac_f32_e32 v161, v43, v3
	v_fmac_f32_e32 v161, v44, v4
	v_fmac_f32_e32 v161, v45, v5
	v_fmac_f32_e32 v161, v46, v6
	v_fmac_f32_e32 v161, v47, v7
	global_load_dwordx4 v[40:43], v24, s[4:5] offset:2048
	global_load_dwordx4 v[44:47], v24, s[4:5] offset:2064
	s_waitcnt vmcnt(30)
	v_mul_f32_e32 v162, v48, v0
	v_fmac_f32_e32 v162, v49, v1
	v_fmac_f32_e32 v162, v50, v2
	v_fmac_f32_e32 v162, v51, v3
	v_fmac_f32_e32 v162, v52, v4
	v_fmac_f32_e32 v162, v53, v5
	v_fmac_f32_e32 v162, v54, v6
	v_fmac_f32_e32 v162, v55, v7
	global_load_dwordx4 v[48:51], v25, s[4:5]
	global_load_dwordx4 v[52:55], v25, s[4:5] offset:16
	s_waitcnt vmcnt(30)
	v_mul_f32_e32 v163, v56, v0
	v_fmac_f32_e32 v163, v57, v1
	v_fmac_f32_e32 v163, v58, v2
	v_fmac_f32_e32 v163, v59, v3
	v_fmac_f32_e32 v163, v60, v4
	v_fmac_f32_e32 v163, v61, v5
	v_fmac_f32_e32 v163, v62, v6
	v_fmac_f32_e32 v163, v63, v7
	global_load_dwordx4 v[56:59], v25, s[4:5] offset:2048
	global_load_dwordx4 v[60:63], v25, s[4:5] offset:2064
	s_waitcnt vmcnt(30)
	v_mul_f32_e32 v164, v64, v0
	v_fmac_f32_e32 v164, v65, v1
	v_fmac_f32_e32 v164, v66, v2
	v_fmac_f32_e32 v164, v67, v3
	v_fmac_f32_e32 v164, v68, v4
	v_fmac_f32_e32 v164, v69, v5
	v_fmac_f32_e32 v164, v70, v6
	v_fmac_f32_e32 v164, v71, v7
	global_load_dwordx4 v[64:67], v26, s[4:5]
	global_load_dwordx4 v[68:71], v26, s[4:5] offset:16
	s_waitcnt vmcnt(30)
	v_mul_f32_e32 v165, v72, v0
	v_fmac_f32_e32 v165, v73, v1
	v_fmac_f32_e32 v165, v74, v2
	v_fmac_f32_e32 v165, v75, v3
	v_fmac_f32_e32 v165, v76, v4
	v_fmac_f32_e32 v165, v77, v5
	v_fmac_f32_e32 v165, v78, v6
	v_fmac_f32_e32 v165, v79, v7
	global_load_dwordx4 v[72:75], v26, s[4:5] offset:2048
	global_load_dwordx4 v[76:79], v26, s[4:5] offset:2064
	s_waitcnt vmcnt(30)
	v_mul_f32_e32 v166, v80, v0
	v_fmac_f32_e32 v166, v81, v1
	v_fmac_f32_e32 v166, v82, v2
	v_fmac_f32_e32 v166, v83, v3
	v_fmac_f32_e32 v166, v84, v4
	v_fmac_f32_e32 v166, v85, v5
	v_fmac_f32_e32 v166, v86, v6
	v_fmac_f32_e32 v166, v87, v7
	global_load_dwordx4 v[80:83], v27, s[4:5]
	global_load_dwordx4 v[84:87], v27, s[4:5] offset:16
	s_waitcnt vmcnt(30)
	v_mul_f32_e32 v167, v88, v0
	v_fmac_f32_e32 v167, v89, v1
	v_fmac_f32_e32 v167, v90, v2
	v_fmac_f32_e32 v167, v91, v3
	v_fmac_f32_e32 v167, v92, v4
	v_fmac_f32_e32 v167, v93, v5
	v_fmac_f32_e32 v167, v94, v6
	v_fmac_f32_e32 v167, v95, v7
	global_load_dwordx4 v[88:91], v27, s[4:5] offset:2048
	global_load_dwordx4 v[92:95], v27, s[4:5] offset:2064
	s_waitcnt vmcnt(30)
	v_mul_f32_e32 v168, v96, v0
	v_fmac_f32_e32 v168, v97, v1
	v_fmac_f32_e32 v168, v98, v2
	v_fmac_f32_e32 v168, v99, v3
	v_fmac_f32_e32 v168, v100, v4
	v_fmac_f32_e32 v168, v101, v5
	v_fmac_f32_e32 v168, v102, v6
	v_fmac_f32_e32 v168, v103, v7
	global_load_dwordx4 v[96:99], v28, s[4:5]
	global_load_dwordx4 v[100:103], v28, s[4:5] offset:16
	s_waitcnt vmcnt(30)
	v_mul_f32_e32 v169, v104, v0
	v_fmac_f32_e32 v169, v105, v1
	v_fmac_f32_e32 v169, v106, v2
	v_fmac_f32_e32 v169, v107, v3
	v_fmac_f32_e32 v169, v108, v4
	v_fmac_f32_e32 v169, v109, v5
	v_fmac_f32_e32 v169, v110, v6
	v_fmac_f32_e32 v169, v111, v7
	global_load_dwordx4 v[104:107], v28, s[4:5] offset:2048
	global_load_dwordx4 v[108:111], v28, s[4:5] offset:2064
	s_waitcnt vmcnt(30)
	v_mul_f32_e32 v170, v112, v0
	v_fmac_f32_e32 v170, v113, v1
	v_fmac_f32_e32 v170, v114, v2
	v_fmac_f32_e32 v170, v115, v3
	v_fmac_f32_e32 v170, v116, v4
	v_fmac_f32_e32 v170, v117, v5
	v_fmac_f32_e32 v170, v118, v6
	v_fmac_f32_e32 v170, v119, v7
	global_load_dwordx4 v[112:115], v29, s[4:5]
	global_load_dwordx4 v[116:119], v29, s[4:5] offset:16
	s_waitcnt vmcnt(30)
	v_mul_f32_e32 v171, v120, v0
	v_fmac_f32_e32 v171, v121, v1
	v_fmac_f32_e32 v171, v122, v2
	v_fmac_f32_e32 v171, v123, v3
	v_fmac_f32_e32 v171, v124, v4
	v_fmac_f32_e32 v171, v125, v5
	v_fmac_f32_e32 v171, v126, v6
	v_fmac_f32_e32 v171, v127, v7
	global_load_dwordx4 v[120:123], v29, s[4:5] offset:2048
	global_load_dwordx4 v[124:127], v29, s[4:5] offset:2064
	s_waitcnt vmcnt(30)
	v_mul_f32_e32 v172, v128, v0
	v_fmac_f32_e32 v172, v129, v1
	v_fmac_f32_e32 v172, v130, v2
	v_fmac_f32_e32 v172, v131, v3
	v_fmac_f32_e32 v172, v132, v4
	v_fmac_f32_e32 v172, v133, v5
	v_fmac_f32_e32 v172, v134, v6
	v_fmac_f32_e32 v172, v135, v7
	global_load_dwordx4 v[128:131], v30, s[4:5]
	global_load_dwordx4 v[132:135], v30, s[4:5] offset:16
	s_waitcnt vmcnt(30)
	v_mul_f32_e32 v173, v136, v0
	v_fmac_f32_e32 v173, v137, v1
	v_fmac_f32_e32 v173, v138, v2
	v_fmac_f32_e32 v173, v139, v3
	v_fmac_f32_e32 v173, v140, v4
	v_fmac_f32_e32 v173, v141, v5
	v_fmac_f32_e32 v173, v142, v6
	v_fmac_f32_e32 v173, v143, v7
	global_load_dwordx4 v[136:139], v30, s[4:5] offset:2048
	global_load_dwordx4 v[140:143], v30, s[4:5] offset:2064
	s_waitcnt vmcnt(30)
	v_mul_f32_e32 v174, v144, v0
	v_fmac_f32_e32 v174, v145, v1
	v_fmac_f32_e32 v174, v146, v2
	v_fmac_f32_e32 v174, v147, v3
	v_fmac_f32_e32 v174, v148, v4
	v_fmac_f32_e32 v174, v149, v5
	v_fmac_f32_e32 v174, v150, v6
	v_fmac_f32_e32 v174, v151, v7
	global_load_dwordx4 v[144:147], v31, s[4:5]
	global_load_dwordx4 v[148:151], v31, s[4:5] offset:16
	s_waitcnt vmcnt(30)
	v_mul_f32_e32 v175, v152, v0
	v_fmac_f32_e32 v175, v153, v1
	v_fmac_f32_e32 v175, v154, v2
	v_fmac_f32_e32 v175, v155, v3
	v_fmac_f32_e32 v175, v156, v4
	v_fmac_f32_e32 v175, v157, v5
	v_fmac_f32_e32 v175, v158, v6
	v_fmac_f32_e32 v175, v159, v7
	global_load_dwordx4 v[152:155], v31, s[4:5] offset:2048
	global_load_dwordx4 v[156:159], v31, s[4:5] offset:2064
	v_add_f32_dpp v160, v160, v160 row_ror:8 row_mask:0xf bank_mask:0x3
	v_add_f32_dpp v160, v168, v168 row_ror:8 row_mask:0xf bank_mask:0xc
	v_add_f32_dpp v161, v161, v161 row_ror:8 row_mask:0xf bank_mask:0x3
	v_add_f32_dpp v161, v169, v169 row_ror:8 row_mask:0xf bank_mask:0xc
	v_add_f32_dpp v162, v162, v162 row_ror:8 row_mask:0xf bank_mask:0x3
	v_add_f32_dpp v162, v170, v170 row_ror:8 row_mask:0xf bank_mask:0xc
	v_add_f32_dpp v163, v163, v163 row_ror:8 row_mask:0xf bank_mask:0x3
	v_add_f32_dpp v163, v171, v171 row_ror:8 row_mask:0xf bank_mask:0xc
	v_add_f32_dpp v164, v164, v164 row_ror:8 row_mask:0xf bank_mask:0x3
	v_add_f32_dpp v164, v172, v172 row_ror:8 row_mask:0xf bank_mask:0xc
	v_add_f32_dpp v165, v165, v165 row_ror:8 row_mask:0xf bank_mask:0x3
	v_add_f32_dpp v165, v173, v173 row_ror:8 row_mask:0xf bank_mask:0xc
	v_add_f32_dpp v166, v166, v166 row_ror:8 row_mask:0xf bank_mask:0x3
	v_add_f32_dpp v166, v174, v174 row_ror:8 row_mask:0xf bank_mask:0xc
	v_add_f32_dpp v167, v167, v167 row_ror:8 row_mask:0xf bank_mask:0x3
	v_add_f32_dpp v167, v175, v175 row_ror:8 row_mask:0xf bank_mask:0xc
	v_add_f32_dpp v160, v160, v160 row_shl:4 row_mask:0xf bank_mask:0x5
	v_add_f32_dpp v160, v164, v164 row_shr:4 row_mask:0xf bank_mask:0xa
	v_add_f32_dpp v161, v161, v161 row_shl:4 row_mask:0xf bank_mask:0x5
	v_add_f32_dpp v161, v165, v165 row_shr:4 row_mask:0xf bank_mask:0xa
	v_add_f32_dpp v162, v162, v162 row_shl:4 row_mask:0xf bank_mask:0x5
	v_add_f32_dpp v162, v166, v166 row_shr:4 row_mask:0xf bank_mask:0xa
	v_add_f32_dpp v163, v163, v163 row_shl:4 row_mask:0xf bank_mask:0x5
	v_add_f32_dpp v163, v167, v167 row_shr:4 row_mask:0xf bank_mask:0xa
	v_and_b32_e32 v176, 2, v18
	v_cmp_ne_u32_e32 vcc, 0, v176
	v_add_f32_dpp v230, v160, v160 quad_perm:[2,3,0,1] row_mask:0xf bank_mask:0xf
	v_add_f32_dpp v231, v162, v162 quad_perm:[2,3,0,1] row_mask:0xf bank_mask:0xf
	v_add_f32_dpp v232, v161, v161 quad_perm:[2,3,0,1] row_mask:0xf bank_mask:0xf
	v_add_f32_dpp v233, v163, v163 quad_perm:[2,3,0,1] row_mask:0xf bank_mask:0xf
	v_cndmask_b32_e32 v230, v230, v231, vcc
	v_cndmask_b32_e32 v232, v232, v233, vcc
	v_and_b32_e32 v176, 1, v18
	v_cmp_ne_u32_e32 vcc, 0, v176
	v_add_f32_dpp v231, v230, v230 quad_perm:[1,0,3,2] row_mask:0xf bank_mask:0xf
	v_add_f32_dpp v233, v232, v232 quad_perm:[1,0,3,2] row_mask:0xf bank_mask:0xf
	s_nop 1
	v_cndmask_b32_e32 v241, v231, v233, vcc
	s_nop 1
	v_max_f32_dpp v242, v241, v241 row_ror:8 row_mask:0xf bank_mask:0xf
	s_nop 1
	v_max_f32_dpp v242, v242, v242 row_ror:4 row_mask:0xf bank_mask:0xf
	s_nop 1
	v_max_f32_dpp v242, v242, v242 row_ror:2 row_mask:0xf bank_mask:0xf
	s_nop 1
	v_max_f32_dpp v242, v242, v242 row_ror:1 row_mask:0xf bank_mask:0xf
	ds_bpermute_b32 v234, v238, v242
	s_waitcnt lgkmcnt(0)
	v_max_f32_e32 v242, v242, v234
	ds_bpermute_b32 v234, v239, v242
	s_waitcnt lgkmcnt(0)
	v_max_f32_e32 v242, v242, v234
	v_max_f32_e32 v242, v16, v242
	v_sub_f32_e32 v243, v16, v242
	v_sub_f32_e32 v240, v241, v242
	v_mul_f32_e32 v243, 0x3fb8aa3b, v243
	v_mul_f32_e32 v240, 0x3fb8aa3b, v240
	v_exp_f32_e32 v243, v243
	v_exp_f32_e32 v240, v240
	v_mov_b32_e32 v16, v242
	s_nop 0
	s_nop 1
	v_add_f32_dpp v235, v240, v240 row_ror:8 row_mask:0xf bank_mask:0xf
	s_nop 1
	v_add_f32_dpp v235, v235, v235 row_ror:4 row_mask:0xf bank_mask:0xf
	s_nop 1
	v_add_f32_dpp v235, v235, v235 row_ror:2 row_mask:0xf bank_mask:0xf
	s_nop 1
	v_add_f32_dpp v235, v235, v235 row_ror:1 row_mask:0xf bank_mask:0xf
	ds_bpermute_b32 v234, v238, v235
	s_waitcnt lgkmcnt(0)
	v_add_f32_e32 v235, v235, v234
	ds_bpermute_b32 v234, v239, v235
	s_waitcnt lgkmcnt(0)
	v_add_f32_e32 v235, v235, v234
	v_fma_f32 v17, v17, v243, v235
	v_mul_f32_e32 v8, v8, v243
	v_mul_f32_e32 v9, v9, v243
	v_mul_f32_e32 v10, v10, v243
	v_mul_f32_e32 v11, v11, v243
	v_mul_f32_e32 v12, v12, v243
	v_mul_f32_e32 v13, v13, v243
	v_mul_f32_e32 v14, v14, v243
	v_mul_f32_e32 v15, v15, v243
	s_add_u32 s2, s2, 0x20000
	s_addc_u32 s3, s3, 0
	s_add_u32 s4, s4, 0x20000
	s_addc_u32 s5, s5, 0
	s_waitcnt vmcnt(30)
	v_fmac_f32_dpp v8, v240, v32 row_newbcast:0 row_mask:0xf bank_mask:0xf
	v_fmac_f32_dpp v9, v240, v33 row_newbcast:0 row_mask:0xf bank_mask:0xf
	v_fmac_f32_dpp v10, v240, v34 row_newbcast:0 row_mask:0xf bank_mask:0xf
	v_fmac_f32_dpp v11, v240, v35 row_newbcast:0 row_mask:0xf bank_mask:0xf
	v_fmac_f32_dpp v12, v240, v36 row_newbcast:0 row_mask:0xf bank_mask:0xf
	v_fmac_f32_dpp v13, v240, v37 row_newbcast:0 row_mask:0xf bank_mask:0xf
	v_fmac_f32_dpp v14, v240, v38 row_newbcast:0 row_mask:0xf bank_mask:0xf
	v_fmac_f32_dpp v15, v240, v39 row_newbcast:0 row_mask:0xf bank_mask:0xf
	global_load_dwordx4 v[32:35], v24, s[2:3]
	global_load_dwordx4 v[36:39], v24, s[2:3] offset:16
	s_waitcnt vmcnt(30)
	v_fmac_f32_dpp v8, v240, v40 row_newbcast:1 row_mask:0xf bank_mask:0xf
	v_fmac_f32_dpp v9, v240, v41 row_newbcast:1 row_mask:0xf bank_mask:0xf
	v_fmac_f32_dpp v10, v240, v42 row_newbcast:1 row_mask:0xf bank_mask:0xf
	v_fmac_f32_dpp v11, v240, v43 row_newbcast:1 row_mask:0xf bank_mask:0xf
	v_fmac_f32_dpp v12, v240, v44 row_newbcast:1 row_mask:0xf bank_mask:0xf
	v_fmac_f32_dpp v13, v240, v45 row_newbcast:1 row_mask:0xf bank_mask:0xf
	v_fmac_f32_dpp v14, v240, v46 row_newbcast:1 row_mask:0xf bank_mask:0xf
	v_fmac_f32_dpp v15, v240, v47 row_newbcast:1 row_mask:0xf bank_mask:0xf
	global_load_dwordx4 v[40:43], v24, s[2:3] offset:2048
	global_load_dwordx4 v[44:47], v24, s[2:3] offset:2064
	s_waitcnt vmcnt(30)
	v_fmac_f32_dpp v8, v240, v48 row_newbcast:2 row_mask:0xf bank_mask:0xf
	v_fmac_f32_dpp v9, v240, v49 row_newbcast:2 row_mask:0xf bank_mask:0xf
	v_fmac_f32_dpp v10, v240, v50 row_newbcast:2 row_mask:0xf bank_mask:0xf
	v_fmac_f32_dpp v11, v240, v51 row_newbcast:2 row_mask:0xf bank_mask:0xf
	v_fmac_f32_dpp v12, v240, v52 row_newbcast:2 row_mask:0xf bank_mask:0xf
	v_fmac_f32_dpp v13, v240, v53 row_newbcast:2 row_mask:0xf bank_mask:0xf
	v_fmac_f32_dpp v14, v240, v54 row_newbcast:2 row_mask:0xf bank_mask:0xf
	v_fmac_f32_dpp v15, v240, v55 row_newbcast:2 row_mask:0xf bank_mask:0xf
	global_load_dwordx4 v[48:51], v25, s[2:3]
	global_load_dwordx4 v[52:55], v25, s[2:3] offset:16
	s_waitcnt vmcnt(30)
	v_fmac_f32_dpp v8, v240, v56 row_newbcast:3 row_mask:0xf bank_mask:0xf
	v_fmac_f32_dpp v9, v240, v57 row_newbcast:3 row_mask:0xf bank_mask:0xf
	v_fmac_f32_dpp v10, v240, v58 row_newbcast:3 row_mask:0xf bank_mask:0xf
	v_fmac_f32_dpp v11, v240, v59 row_newbcast:3 row_mask:0xf bank_mask:0xf
	v_fmac_f32_dpp v12, v240, v60 row_newbcast:3 row_mask:0xf bank_mask:0xf
	v_fmac_f32_dpp v13, v240, v61 row_newbcast:3 row_mask:0xf bank_mask:0xf
	v_fmac_f32_dpp v14, v240, v62 row_newbcast:3 row_mask:0xf bank_mask:0xf
	v_fmac_f32_dpp v15, v240, v63 row_newbcast:3 row_mask:0xf bank_mask:0xf
	global_load_dwordx4 v[56:59], v25, s[2:3] offset:2048
	global_load_dwordx4 v[60:63], v25, s[2:3] offset:2064
	s_waitcnt vmcnt(30)
	v_fmac_f32_dpp v8, v240, v64 row_newbcast:4 row_mask:0xf bank_mask:0xf
	v_fmac_f32_dpp v9, v240, v65 row_newbcast:4 row_mask:0xf bank_mask:0xf
	v_fmac_f32_dpp v10, v240, v66 row_newbcast:4 row_mask:0xf bank_mask:0xf
	v_fmac_f32_dpp v11, v240, v67 row_newbcast:4 row_mask:0xf bank_mask:0xf
	v_fmac_f32_dpp v12, v240, v68 row_newbcast:4 row_mask:0xf bank_mask:0xf
	v_fmac_f32_dpp v13, v240, v69 row_newbcast:4 row_mask:0xf bank_mask:0xf
	v_fmac_f32_dpp v14, v240, v70 row_newbcast:4 row_mask:0xf bank_mask:0xf
	v_fmac_f32_dpp v15, v240, v71 row_newbcast:4 row_mask:0xf bank_mask:0xf
	global_load_dwordx4 v[64:67], v26, s[2:3]
	global_load_dwordx4 v[68:71], v26, s[2:3] offset:16
	s_waitcnt vmcnt(30)
	v_fmac_f32_dpp v8, v240, v72 row_newbcast:5 row_mask:0xf bank_mask:0xf
	v_fmac_f32_dpp v9, v240, v73 row_newbcast:5 row_mask:0xf bank_mask:0xf
	v_fmac_f32_dpp v10, v240, v74 row_newbcast:5 row_mask:0xf bank_mask:0xf
	v_fmac_f32_dpp v11, v240, v75 row_newbcast:5 row_mask:0xf bank_mask:0xf
	v_fmac_f32_dpp v12, v240, v76 row_newbcast:5 row_mask:0xf bank_mask:0xf
	v_fmac_f32_dpp v13, v240, v77 row_newbcast:5 row_mask:0xf bank_mask:0xf
	v_fmac_f32_dpp v14, v240, v78 row_newbcast:5 row_mask:0xf bank_mask:0xf
	v_fmac_f32_dpp v15, v240, v79 row_newbcast:5 row_mask:0xf bank_mask:0xf
	global_load_dwordx4 v[72:75], v26, s[2:3] offset:2048
	global_load_dwordx4 v[76:79], v26, s[2:3] offset:2064
	s_waitcnt vmcnt(30)
	v_fmac_f32_dpp v8, v240, v80 row_newbcast:6 row_mask:0xf bank_mask:0xf
	v_fmac_f32_dpp v9, v240, v81 row_newbcast:6 row_mask:0xf bank_mask:0xf
	v_fmac_f32_dpp v10, v240, v82 row_newbcast:6 row_mask:0xf bank_mask:0xf
	v_fmac_f32_dpp v11, v240, v83 row_newbcast:6 row_mask:0xf bank_mask:0xf
	v_fmac_f32_dpp v12, v240, v84 row_newbcast:6 row_mask:0xf bank_mask:0xf
	v_fmac_f32_dpp v13, v240, v85 row_newbcast:6 row_mask:0xf bank_mask:0xf
	v_fmac_f32_dpp v14, v240, v86 row_newbcast:6 row_mask:0xf bank_mask:0xf
	v_fmac_f32_dpp v15, v240, v87 row_newbcast:6 row_mask:0xf bank_mask:0xf
	global_load_dwordx4 v[80:83], v27, s[2:3]
	global_load_dwordx4 v[84:87], v27, s[2:3] offset:16
	s_waitcnt vmcnt(30)
	v_fmac_f32_dpp v8, v240, v88 row_newbcast:7 row_mask:0xf bank_mask:0xf
	v_fmac_f32_dpp v9, v240, v89 row_newbcast:7 row_mask:0xf bank_mask:0xf
	v_fmac_f32_dpp v10, v240, v90 row_newbcast:7 row_mask:0xf bank_mask:0xf
	v_fmac_f32_dpp v11, v240, v91 row_newbcast:7 row_mask:0xf bank_mask:0xf
	v_fmac_f32_dpp v12, v240, v92 row_newbcast:7 row_mask:0xf bank_mask:0xf
	v_fmac_f32_dpp v13, v240, v93 row_newbcast:7 row_mask:0xf bank_mask:0xf
	v_fmac_f32_dpp v14, v240, v94 row_newbcast:7 row_mask:0xf bank_mask:0xf
	v_fmac_f32_dpp v15, v240, v95 row_newbcast:7 row_mask:0xf bank_mask:0xf
	global_load_dwordx4 v[88:91], v27, s[2:3] offset:2048
	global_load_dwordx4 v[92:95], v27, s[2:3] offset:2064
	s_waitcnt vmcnt(30)
	v_fmac_f32_dpp v8, v240, v96 row_newbcast:8 row_mask:0xf bank_mask:0xf
	v_fmac_f32_dpp v9, v240, v97 row_newbcast:8 row_mask:0xf bank_mask:0xf
	v_fmac_f32_dpp v10, v240, v98 row_newbcast:8 row_mask:0xf bank_mask:0xf
	v_fmac_f32_dpp v11, v240, v99 row_newbcast:8 row_mask:0xf bank_mask:0xf
	v_fmac_f32_dpp v12, v240, v100 row_newbcast:8 row_mask:0xf bank_mask:0xf
	v_fmac_f32_dpp v13, v240, v101 row_newbcast:8 row_mask:0xf bank_mask:0xf
	v_fmac_f32_dpp v14, v240, v102 row_newbcast:8 row_mask:0xf bank_mask:0xf
	v_fmac_f32_dpp v15, v240, v103 row_newbcast:8 row_mask:0xf bank_mask:0xf
	global_load_dwordx4 v[96:99], v28, s[2:3]
	global_load_dwordx4 v[100:103], v28, s[2:3] offset:16
	s_waitcnt vmcnt(30)
	v_fmac_f32_dpp v8, v240, v104 row_newbcast:9 row_mask:0xf bank_mask:0xf
	v_fmac_f32_dpp v9, v240, v105 row_newbcast:9 row_mask:0xf bank_mask:0xf
	v_fmac_f32_dpp v10, v240, v106 row_newbcast:9 row_mask:0xf bank_mask:0xf
	v_fmac_f32_dpp v11, v240, v107 row_newbcast:9 row_mask:0xf bank_mask:0xf
	v_fmac_f32_dpp v12, v240, v108 row_newbcast:9 row_mask:0xf bank_mask:0xf
	v_fmac_f32_dpp v13, v240, v109 row_newbcast:9 row_mask:0xf bank_mask:0xf
	v_fmac_f32_dpp v14, v240, v110 row_newbcast:9 row_mask:0xf bank_mask:0xf
	v_fmac_f32_dpp v15, v240, v111 row_newbcast:9 row_mask:0xf bank_mask:0xf
	global_load_dwordx4 v[104:107], v28, s[2:3] offset:2048
	global_load_dwordx4 v[108:111], v28, s[2:3] offset:2064
	s_waitcnt vmcnt(30)
	v_fmac_f32_dpp v8, v240, v112 row_newbcast:10 row_mask:0xf bank_mask:0xf
	v_fmac_f32_dpp v9, v240, v113 row_newbcast:10 row_mask:0xf bank_mask:0xf
	v_fmac_f32_dpp v10, v240, v114 row_newbcast:10 row_mask:0xf bank_mask:0xf
	v_fmac_f32_dpp v11, v240, v115 row_newbcast:10 row_mask:0xf bank_mask:0xf
	v_fmac_f32_dpp v12, v240, v116 row_newbcast:10 row_mask:0xf bank_mask:0xf
	v_fmac_f32_dpp v13, v240, v117 row_newbcast:10 row_mask:0xf bank_mask:0xf
	v_fmac_f32_dpp v14, v240, v118 row_newbcast:10 row_mask:0xf bank_mask:0xf
	v_fmac_f32_dpp v15, v240, v119 row_newbcast:10 row_mask:0xf bank_mask:0xf
	global_load_dwordx4 v[112:115], v29, s[2:3]
	global_load_dwordx4 v[116:119], v29, s[2:3] offset:16
	s_waitcnt vmcnt(30)
	v_fmac_f32_dpp v8, v240, v120 row_newbcast:11 row_mask:0xf bank_mask:0xf
	v_fmac_f32_dpp v9, v240, v121 row_newbcast:11 row_mask:0xf bank_mask:0xf
	v_fmac_f32_dpp v10, v240, v122 row_newbcast:11 row_mask:0xf bank_mask:0xf
	v_fmac_f32_dpp v11, v240, v123 row_newbcast:11 row_mask:0xf bank_mask:0xf
	v_fmac_f32_dpp v12, v240, v124 row_newbcast:11 row_mask:0xf bank_mask:0xf
	v_fmac_f32_dpp v13, v240, v125 row_newbcast:11 row_mask:0xf bank_mask:0xf
	v_fmac_f32_dpp v14, v240, v126 row_newbcast:11 row_mask:0xf bank_mask:0xf
	v_fmac_f32_dpp v15, v240, v127 row_newbcast:11 row_mask:0xf bank_mask:0xf
	global_load_dwordx4 v[120:123], v29, s[2:3] offset:2048
	global_load_dwordx4 v[124:127], v29, s[2:3] offset:2064
	s_waitcnt vmcnt(30)
	v_fmac_f32_dpp v8, v240, v128 row_newbcast:12 row_mask:0xf bank_mask:0xf
	v_fmac_f32_dpp v9, v240, v129 row_newbcast:12 row_mask:0xf bank_mask:0xf
	v_fmac_f32_dpp v10, v240, v130 row_newbcast:12 row_mask:0xf bank_mask:0xf
	v_fmac_f32_dpp v11, v240, v131 row_newbcast:12 row_mask:0xf bank_mask:0xf
	v_fmac_f32_dpp v12, v240, v132 row_newbcast:12 row_mask:0xf bank_mask:0xf
	v_fmac_f32_dpp v13, v240, v133 row_newbcast:12 row_mask:0xf bank_mask:0xf
	v_fmac_f32_dpp v14, v240, v134 row_newbcast:12 row_mask:0xf bank_mask:0xf
	v_fmac_f32_dpp v15, v240, v135 row_newbcast:12 row_mask:0xf bank_mask:0xf
	global_load_dwordx4 v[128:131], v30, s[2:3]
	global_load_dwordx4 v[132:135], v30, s[2:3] offset:16
	s_waitcnt vmcnt(30)
	v_fmac_f32_dpp v8, v240, v136 row_newbcast:13 row_mask:0xf bank_mask:0xf
	v_fmac_f32_dpp v9, v240, v137 row_newbcast:13 row_mask:0xf bank_mask:0xf
	v_fmac_f32_dpp v10, v240, v138 row_newbcast:13 row_mask:0xf bank_mask:0xf
	v_fmac_f32_dpp v11, v240, v139 row_newbcast:13 row_mask:0xf bank_mask:0xf
	v_fmac_f32_dpp v12, v240, v140 row_newbcast:13 row_mask:0xf bank_mask:0xf
	v_fmac_f32_dpp v13, v240, v141 row_newbcast:13 row_mask:0xf bank_mask:0xf
	v_fmac_f32_dpp v14, v240, v142 row_newbcast:13 row_mask:0xf bank_mask:0xf
	v_fmac_f32_dpp v15, v240, v143 row_newbcast:13 row_mask:0xf bank_mask:0xf
	global_load_dwordx4 v[136:139], v30, s[2:3] offset:2048
	global_load_dwordx4 v[140:143], v30, s[2:3] offset:2064
	s_waitcnt vmcnt(30)
	v_fmac_f32_dpp v8, v240, v144 row_newbcast:14 row_mask:0xf bank_mask:0xf
	v_fmac_f32_dpp v9, v240, v145 row_newbcast:14 row_mask:0xf bank_mask:0xf
	v_fmac_f32_dpp v10, v240, v146 row_newbcast:14 row_mask:0xf bank_mask:0xf
	v_fmac_f32_dpp v11, v240, v147 row_newbcast:14 row_mask:0xf bank_mask:0xf
	v_fmac_f32_dpp v12, v240, v148 row_newbcast:14 row_mask:0xf bank_mask:0xf
	v_fmac_f32_dpp v13, v240, v149 row_newbcast:14 row_mask:0xf bank_mask:0xf
	v_fmac_f32_dpp v14, v240, v150 row_newbcast:14 row_mask:0xf bank_mask:0xf
	v_fmac_f32_dpp v15, v240, v151 row_newbcast:14 row_mask:0xf bank_mask:0xf
	global_load_dwordx4 v[144:147], v31, s[2:3]
	global_load_dwordx4 v[148:151], v31, s[2:3] offset:16
	s_waitcnt vmcnt(30)
	v_fmac_f32_dpp v8, v240, v152 row_newbcast:15 row_mask:0xf bank_mask:0xf
	v_fmac_f32_dpp v9, v240, v153 row_newbcast:15 row_mask:0xf bank_mask:0xf
	v_fmac_f32_dpp v10, v240, v154 row_newbcast:15 row_mask:0xf bank_mask:0xf
	v_fmac_f32_dpp v11, v240, v155 row_newbcast:15 row_mask:0xf bank_mask:0xf
	v_fmac_f32_dpp v12, v240, v156 row_newbcast:15 row_mask:0xf bank_mask:0xf
	v_fmac_f32_dpp v13, v240, v157 row_newbcast:15 row_mask:0xf bank_mask:0xf
	v_fmac_f32_dpp v14, v240, v158 row_newbcast:15 row_mask:0xf bank_mask:0xf
	v_fmac_f32_dpp v15, v240, v159 row_newbcast:15 row_mask:0xf bank_mask:0xf
	global_load_dwordx4 v[152:155], v31, s[2:3] offset:2048
	global_load_dwordx4 v[156:159], v31, s[2:3] offset:2064
	s_waitcnt vmcnt(30)
	v_mul_f32_e32 v160, v32, v0
	v_fmac_f32_e32 v160, v33, v1
	v_fmac_f32_e32 v160, v34, v2
	v_fmac_f32_e32 v160, v35, v3
	v_fmac_f32_e32 v160, v36, v4
	v_fmac_f32_e32 v160, v37, v5
	v_fmac_f32_e32 v160, v38, v6
	v_fmac_f32_e32 v160, v39, v7
	global_load_dwordx4 v[32:35], v24, s[4:5]
	global_load_dwordx4 v[36:39], v24, s[4:5] offset:16
	s_waitcnt vmcnt(30)
	v_mul_f32_e32 v161, v40, v0
	v_fmac_f32_e32 v161, v41, v1
	v_fmac_f32_e32 v161, v42, v2
	v_fmac_f32_e32 v161, v43, v3
	v_fmac_f32_e32 v161, v44, v4
	v_fmac_f32_e32 v161, v45, v5
	v_fmac_f32_e32 v161, v46, v6
	v_fmac_f32_e32 v161, v47, v7
	global_load_dwordx4 v[40:43], v24, s[4:5] offset:2048
	global_load_dwordx4 v[44:47], v24, s[4:5] offset:2064
	s_waitcnt vmcnt(30)
	v_mul_f32_e32 v162, v48, v0
	v_fmac_f32_e32 v162, v49, v1
	v_fmac_f32_e32 v162, v50, v2
	v_fmac_f32_e32 v162, v51, v3
	v_fmac_f32_e32 v162, v52, v4
	v_fmac_f32_e32 v162, v53, v5
	v_fmac_f32_e32 v162, v54, v6
	v_fmac_f32_e32 v162, v55, v7
	global_load_dwordx4 v[48:51], v25, s[4:5]
	global_load_dwordx4 v[52:55], v25, s[4:5] offset:16
	s_waitcnt vmcnt(30)
	v_mul_f32_e32 v163, v56, v0
	v_fmac_f32_e32 v163, v57, v1
	v_fmac_f32_e32 v163, v58, v2
	v_fmac_f32_e32 v163, v59, v3
	v_fmac_f32_e32 v163, v60, v4
	v_fmac_f32_e32 v163, v61, v5
	v_fmac_f32_e32 v163, v62, v6
	v_fmac_f32_e32 v163, v63, v7
	global_load_dwordx4 v[56:59], v25, s[4:5] offset:2048
	global_load_dwordx4 v[60:63], v25, s[4:5] offset:2064
	s_waitcnt vmcnt(30)
	v_mul_f32_e32 v164, v64, v0
	v_fmac_f32_e32 v164, v65, v1
	v_fmac_f32_e32 v164, v66, v2
	v_fmac_f32_e32 v164, v67, v3
	v_fmac_f32_e32 v164, v68, v4
	v_fmac_f32_e32 v164, v69, v5
	v_fmac_f32_e32 v164, v70, v6
	v_fmac_f32_e32 v164, v71, v7
	global_load_dwordx4 v[64:67], v26, s[4:5]
	global_load_dwordx4 v[68:71], v26, s[4:5] offset:16
	s_waitcnt vmcnt(30)
	v_mul_f32_e32 v165, v72, v0
	v_fmac_f32_e32 v165, v73, v1
	v_fmac_f32_e32 v165, v74, v2
	v_fmac_f32_e32 v165, v75, v3
	v_fmac_f32_e32 v165, v76, v4
	v_fmac_f32_e32 v165, v77, v5
	v_fmac_f32_e32 v165, v78, v6
	v_fmac_f32_e32 v165, v79, v7
	global_load_dwordx4 v[72:75], v26, s[4:5] offset:2048
	global_load_dwordx4 v[76:79], v26, s[4:5] offset:2064
	s_waitcnt vmcnt(30)
	v_mul_f32_e32 v166, v80, v0
	v_fmac_f32_e32 v166, v81, v1
	v_fmac_f32_e32 v166, v82, v2
	v_fmac_f32_e32 v166, v83, v3
	v_fmac_f32_e32 v166, v84, v4
	v_fmac_f32_e32 v166, v85, v5
	v_fmac_f32_e32 v166, v86, v6
	v_fmac_f32_e32 v166, v87, v7
	global_load_dwordx4 v[80:83], v27, s[4:5]
	global_load_dwordx4 v[84:87], v27, s[4:5] offset:16
	s_waitcnt vmcnt(30)
	v_mul_f32_e32 v167, v88, v0
	v_fmac_f32_e32 v167, v89, v1
	v_fmac_f32_e32 v167, v90, v2
	v_fmac_f32_e32 v167, v91, v3
	v_fmac_f32_e32 v167, v92, v4
	v_fmac_f32_e32 v167, v93, v5
	v_fmac_f32_e32 v167, v94, v6
	v_fmac_f32_e32 v167, v95, v7
	global_load_dwordx4 v[88:91], v27, s[4:5] offset:2048
	global_load_dwordx4 v[92:95], v27, s[4:5] offset:2064
	s_waitcnt vmcnt(30)
	v_mul_f32_e32 v168, v96, v0
	v_fmac_f32_e32 v168, v97, v1
	v_fmac_f32_e32 v168, v98, v2
	v_fmac_f32_e32 v168, v99, v3
	v_fmac_f32_e32 v168, v100, v4
	v_fmac_f32_e32 v168, v101, v5
	v_fmac_f32_e32 v168, v102, v6
	v_fmac_f32_e32 v168, v103, v7
	global_load_dwordx4 v[96:99], v28, s[4:5]
	global_load_dwordx4 v[100:103], v28, s[4:5] offset:16
	s_waitcnt vmcnt(30)
	v_mul_f32_e32 v169, v104, v0
	v_fmac_f32_e32 v169, v105, v1
	v_fmac_f32_e32 v169, v106, v2
	v_fmac_f32_e32 v169, v107, v3
	v_fmac_f32_e32 v169, v108, v4
	v_fmac_f32_e32 v169, v109, v5
	v_fmac_f32_e32 v169, v110, v6
	v_fmac_f32_e32 v169, v111, v7
	global_load_dwordx4 v[104:107], v28, s[4:5] offset:2048
	global_load_dwordx4 v[108:111], v28, s[4:5] offset:2064
	s_waitcnt vmcnt(30)
	v_mul_f32_e32 v170, v112, v0
	v_fmac_f32_e32 v170, v113, v1
	v_fmac_f32_e32 v170, v114, v2
	v_fmac_f32_e32 v170, v115, v3
	v_fmac_f32_e32 v170, v116, v4
	v_fmac_f32_e32 v170, v117, v5
	v_fmac_f32_e32 v170, v118, v6
	v_fmac_f32_e32 v170, v119, v7
	global_load_dwordx4 v[112:115], v29, s[4:5]
	global_load_dwordx4 v[116:119], v29, s[4:5] offset:16
	s_waitcnt vmcnt(30)
	v_mul_f32_e32 v171, v120, v0
	v_fmac_f32_e32 v171, v121, v1
	v_fmac_f32_e32 v171, v122, v2
	v_fmac_f32_e32 v171, v123, v3
	v_fmac_f32_e32 v171, v124, v4
	v_fmac_f32_e32 v171, v125, v5
	v_fmac_f32_e32 v171, v126, v6
	v_fmac_f32_e32 v171, v127, v7
	global_load_dwordx4 v[120:123], v29, s[4:5] offset:2048
	global_load_dwordx4 v[124:127], v29, s[4:5] offset:2064
	s_waitcnt vmcnt(30)
	v_mul_f32_e32 v172, v128, v0
	v_fmac_f32_e32 v172, v129, v1
	v_fmac_f32_e32 v172, v130, v2
	v_fmac_f32_e32 v172, v131, v3
	v_fmac_f32_e32 v172, v132, v4
	v_fmac_f32_e32 v172, v133, v5
	v_fmac_f32_e32 v172, v134, v6
	v_fmac_f32_e32 v172, v135, v7
	global_load_dwordx4 v[128:131], v30, s[4:5]
	global_load_dwordx4 v[132:135], v30, s[4:5] offset:16
	s_waitcnt vmcnt(30)
	v_mul_f32_e32 v173, v136, v0
	v_fmac_f32_e32 v173, v137, v1
	v_fmac_f32_e32 v173, v138, v2
	v_fmac_f32_e32 v173, v139, v3
	v_fmac_f32_e32 v173, v140, v4
	v_fmac_f32_e32 v173, v141, v5
	v_fmac_f32_e32 v173, v142, v6
	v_fmac_f32_e32 v173, v143, v7
	global_load_dwordx4 v[136:139], v30, s[4:5] offset:2048
	global_load_dwordx4 v[140:143], v30, s[4:5] offset:2064
	s_waitcnt vmcnt(30)
	v_mul_f32_e32 v174, v144, v0
	v_fmac_f32_e32 v174, v145, v1
	v_fmac_f32_e32 v174, v146, v2
	v_fmac_f32_e32 v174, v147, v3
	v_fmac_f32_e32 v174, v148, v4
	v_fmac_f32_e32 v174, v149, v5
	v_fmac_f32_e32 v174, v150, v6
	v_fmac_f32_e32 v174, v151, v7
	global_load_dwordx4 v[144:147], v31, s[4:5]
	global_load_dwordx4 v[148:151], v31, s[4:5] offset:16
	s_waitcnt vmcnt(30)
	v_mul_f32_e32 v175, v152, v0
	v_fmac_f32_e32 v175, v153, v1
	v_fmac_f32_e32 v175, v154, v2
	v_fmac_f32_e32 v175, v155, v3
	v_fmac_f32_e32 v175, v156, v4
	v_fmac_f32_e32 v175, v157, v5
	v_fmac_f32_e32 v175, v158, v6
	v_fmac_f32_e32 v175, v159, v7
	global_load_dwordx4 v[152:155], v31, s[4:5] offset:2048
	global_load_dwordx4 v[156:159], v31, s[4:5] offset:2064
	v_add_f32_dpp v160, v160, v160 row_ror:8 row_mask:0xf bank_mask:0x3
	v_add_f32_dpp v160, v168, v168 row_ror:8 row_mask:0xf bank_mask:0xc
	v_add_f32_dpp v161, v161, v161 row_ror:8 row_mask:0xf bank_mask:0x3
	v_add_f32_dpp v161, v169, v169 row_ror:8 row_mask:0xf bank_mask:0xc
	v_add_f32_dpp v162, v162, v162 row_ror:8 row_mask:0xf bank_mask:0x3
	v_add_f32_dpp v162, v170, v170 row_ror:8 row_mask:0xf bank_mask:0xc
	v_add_f32_dpp v163, v163, v163 row_ror:8 row_mask:0xf bank_mask:0x3
	v_add_f32_dpp v163, v171, v171 row_ror:8 row_mask:0xf bank_mask:0xc
	v_add_f32_dpp v164, v164, v164 row_ror:8 row_mask:0xf bank_mask:0x3
	v_add_f32_dpp v164, v172, v172 row_ror:8 row_mask:0xf bank_mask:0xc
	v_add_f32_dpp v165, v165, v165 row_ror:8 row_mask:0xf bank_mask:0x3
	v_add_f32_dpp v165, v173, v173 row_ror:8 row_mask:0xf bank_mask:0xc
	v_add_f32_dpp v166, v166, v166 row_ror:8 row_mask:0xf bank_mask:0x3
	v_add_f32_dpp v166, v174, v174 row_ror:8 row_mask:0xf bank_mask:0xc
	v_add_f32_dpp v167, v167, v167 row_ror:8 row_mask:0xf bank_mask:0x3
	v_add_f32_dpp v167, v175, v175 row_ror:8 row_mask:0xf bank_mask:0xc
	v_add_f32_dpp v160, v160, v160 row_shl:4 row_mask:0xf bank_mask:0x5
	v_add_f32_dpp v160, v164, v164 row_shr:4 row_mask:0xf bank_mask:0xa
	v_add_f32_dpp v161, v161, v161 row_shl:4 row_mask:0xf bank_mask:0x5
	v_add_f32_dpp v161, v165, v165 row_shr:4 row_mask:0xf bank_mask:0xa
	v_add_f32_dpp v162, v162, v162 row_shl:4 row_mask:0xf bank_mask:0x5
	v_add_f32_dpp v162, v166, v166 row_shr:4 row_mask:0xf bank_mask:0xa
	v_add_f32_dpp v163, v163, v163 row_shl:4 row_mask:0xf bank_mask:0x5
	v_add_f32_dpp v163, v167, v167 row_shr:4 row_mask:0xf bank_mask:0xa
	v_and_b32_e32 v176, 2, v18
	v_cmp_ne_u32_e32 vcc, 0, v176
	v_add_f32_dpp v230, v160, v160 quad_perm:[2,3,0,1] row_mask:0xf bank_mask:0xf
	v_add_f32_dpp v231, v162, v162 quad_perm:[2,3,0,1] row_mask:0xf bank_mask:0xf
	v_add_f32_dpp v232, v161, v161 quad_perm:[2,3,0,1] row_mask:0xf bank_mask:0xf
	v_add_f32_dpp v233, v163, v163 quad_perm:[2,3,0,1] row_mask:0xf bank_mask:0xf
	v_cndmask_b32_e32 v230, v230, v231, vcc
	v_cndmask_b32_e32 v232, v232, v233, vcc
	v_and_b32_e32 v176, 1, v18
	v_cmp_ne_u32_e32 vcc, 0, v176
	v_add_f32_dpp v231, v230, v230 quad_perm:[1,0,3,2] row_mask:0xf bank_mask:0xf
	v_add_f32_dpp v233, v232, v232 quad_perm:[1,0,3,2] row_mask:0xf bank_mask:0xf
	s_nop 1
	v_cndmask_b32_e32 v241, v231, v233, vcc
	s_nop 1
	v_max_f32_dpp v242, v241, v241 row_ror:8 row_mask:0xf bank_mask:0xf
	s_nop 1
	v_max_f32_dpp v242, v242, v242 row_ror:4 row_mask:0xf bank_mask:0xf
	s_nop 1
	v_max_f32_dpp v242, v242, v242 row_ror:2 row_mask:0xf bank_mask:0xf
	s_nop 1
	v_max_f32_dpp v242, v242, v242 row_ror:1 row_mask:0xf bank_mask:0xf
	ds_bpermute_b32 v234, v238, v242
	s_waitcnt lgkmcnt(0)
	v_max_f32_e32 v242, v242, v234
	ds_bpermute_b32 v234, v239, v242
	s_waitcnt lgkmcnt(0)
	v_max_f32_e32 v242, v242, v234
	v_max_f32_e32 v242, v16, v242
	v_sub_f32_e32 v243, v16, v242
	v_sub_f32_e32 v240, v241, v242
	v_mul_f32_e32 v243, 0x3fb8aa3b, v243
	v_mul_f32_e32 v240, 0x3fb8aa3b, v240
	v_exp_f32_e32 v243, v243
	v_exp_f32_e32 v240, v240
	v_mov_b32_e32 v16, v242
	s_nop 0
	s_nop 1
	v_add_f32_dpp v235, v240, v240 row_ror:8 row_mask:0xf bank_mask:0xf
	s_nop 1
	v_add_f32_dpp v235, v235, v235 row_ror:4 row_mask:0xf bank_mask:0xf
	s_nop 1
	v_add_f32_dpp v235, v235, v235 row_ror:2 row_mask:0xf bank_mask:0xf
	s_nop 1
	v_add_f32_dpp v235, v235, v235 row_ror:1 row_mask:0xf bank_mask:0xf
	ds_bpermute_b32 v234, v238, v235
	s_waitcnt lgkmcnt(0)
	v_add_f32_e32 v235, v235, v234
	ds_bpermute_b32 v234, v239, v235
	s_waitcnt lgkmcnt(0)
	v_add_f32_e32 v235, v235, v234
	v_fma_f32 v17, v17, v243, v235
	v_mul_f32_e32 v8, v8, v243
	v_mul_f32_e32 v9, v9, v243
	v_mul_f32_e32 v10, v10, v243
	v_mul_f32_e32 v11, v11, v243
	v_mul_f32_e32 v12, v12, v243
	v_mul_f32_e32 v13, v13, v243
	v_mul_f32_e32 v14, v14, v243
	v_mul_f32_e32 v15, v15, v243
	s_waitcnt vmcnt(30)
	v_fmac_f32_dpp v8, v240, v32 row_newbcast:0 row_mask:0xf bank_mask:0xf
	v_fmac_f32_dpp v9, v240, v33 row_newbcast:0 row_mask:0xf bank_mask:0xf
	v_fmac_f32_dpp v10, v240, v34 row_newbcast:0 row_mask:0xf bank_mask:0xf
	v_fmac_f32_dpp v11, v240, v35 row_newbcast:0 row_mask:0xf bank_mask:0xf
	v_fmac_f32_dpp v12, v240, v36 row_newbcast:0 row_mask:0xf bank_mask:0xf
	v_fmac_f32_dpp v13, v240, v37 row_newbcast:0 row_mask:0xf bank_mask:0xf
	v_fmac_f32_dpp v14, v240, v38 row_newbcast:0 row_mask:0xf bank_mask:0xf
	v_fmac_f32_dpp v15, v240, v39 row_newbcast:0 row_mask:0xf bank_mask:0xf
	s_waitcnt vmcnt(28)
	v_fmac_f32_dpp v8, v240, v40 row_newbcast:1 row_mask:0xf bank_mask:0xf
	v_fmac_f32_dpp v9, v240, v41 row_newbcast:1 row_mask:0xf bank_mask:0xf
	v_fmac_f32_dpp v10, v240, v42 row_newbcast:1 row_mask:0xf bank_mask:0xf
	v_fmac_f32_dpp v11, v240, v43 row_newbcast:1 row_mask:0xf bank_mask:0xf
	v_fmac_f32_dpp v12, v240, v44 row_newbcast:1 row_mask:0xf bank_mask:0xf
	v_fmac_f32_dpp v13, v240, v45 row_newbcast:1 row_mask:0xf bank_mask:0xf
	v_fmac_f32_dpp v14, v240, v46 row_newbcast:1 row_mask:0xf bank_mask:0xf
	v_fmac_f32_dpp v15, v240, v47 row_newbcast:1 row_mask:0xf bank_mask:0xf
	s_waitcnt vmcnt(26)
	v_fmac_f32_dpp v8, v240, v48 row_newbcast:2 row_mask:0xf bank_mask:0xf
	v_fmac_f32_dpp v9, v240, v49 row_newbcast:2 row_mask:0xf bank_mask:0xf
	v_fmac_f32_dpp v10, v240, v50 row_newbcast:2 row_mask:0xf bank_mask:0xf
	v_fmac_f32_dpp v11, v240, v51 row_newbcast:2 row_mask:0xf bank_mask:0xf
	v_fmac_f32_dpp v12, v240, v52 row_newbcast:2 row_mask:0xf bank_mask:0xf
	v_fmac_f32_dpp v13, v240, v53 row_newbcast:2 row_mask:0xf bank_mask:0xf
	v_fmac_f32_dpp v14, v240, v54 row_newbcast:2 row_mask:0xf bank_mask:0xf
	v_fmac_f32_dpp v15, v240, v55 row_newbcast:2 row_mask:0xf bank_mask:0xf
	s_waitcnt vmcnt(24)
	v_fmac_f32_dpp v8, v240, v56 row_newbcast:3 row_mask:0xf bank_mask:0xf
	v_fmac_f32_dpp v9, v240, v57 row_newbcast:3 row_mask:0xf bank_mask:0xf
	v_fmac_f32_dpp v10, v240, v58 row_newbcast:3 row_mask:0xf bank_mask:0xf
	v_fmac_f32_dpp v11, v240, v59 row_newbcast:3 row_mask:0xf bank_mask:0xf
	v_fmac_f32_dpp v12, v240, v60 row_newbcast:3 row_mask:0xf bank_mask:0xf
	v_fmac_f32_dpp v13, v240, v61 row_newbcast:3 row_mask:0xf bank_mask:0xf
	v_fmac_f32_dpp v14, v240, v62 row_newbcast:3 row_mask:0xf bank_mask:0xf
	v_fmac_f32_dpp v15, v240, v63 row_newbcast:3 row_mask:0xf bank_mask:0xf
	s_waitcnt vmcnt(22)
	v_fmac_f32_dpp v8, v240, v64 row_newbcast:4 row_mask:0xf bank_mask:0xf
	v_fmac_f32_dpp v9, v240, v65 row_newbcast:4 row_mask:0xf bank_mask:0xf
	v_fmac_f32_dpp v10, v240, v66 row_newbcast:4 row_mask:0xf bank_mask:0xf
	v_fmac_f32_dpp v11, v240, v67 row_newbcast:4 row_mask:0xf bank_mask:0xf
	v_fmac_f32_dpp v12, v240, v68 row_newbcast:4 row_mask:0xf bank_mask:0xf
	v_fmac_f32_dpp v13, v240, v69 row_newbcast:4 row_mask:0xf bank_mask:0xf
	v_fmac_f32_dpp v14, v240, v70 row_newbcast:4 row_mask:0xf bank_mask:0xf
	v_fmac_f32_dpp v15, v240, v71 row_newbcast:4 row_mask:0xf bank_mask:0xf
	s_waitcnt vmcnt(20)
	v_fmac_f32_dpp v8, v240, v72 row_newbcast:5 row_mask:0xf bank_mask:0xf
	v_fmac_f32_dpp v9, v240, v73 row_newbcast:5 row_mask:0xf bank_mask:0xf
	v_fmac_f32_dpp v10, v240, v74 row_newbcast:5 row_mask:0xf bank_mask:0xf
	v_fmac_f32_dpp v11, v240, v75 row_newbcast:5 row_mask:0xf bank_mask:0xf
	v_fmac_f32_dpp v12, v240, v76 row_newbcast:5 row_mask:0xf bank_mask:0xf
	v_fmac_f32_dpp v13, v240, v77 row_newbcast:5 row_mask:0xf bank_mask:0xf
	v_fmac_f32_dpp v14, v240, v78 row_newbcast:5 row_mask:0xf bank_mask:0xf
	v_fmac_f32_dpp v15, v240, v79 row_newbcast:5 row_mask:0xf bank_mask:0xf
	s_waitcnt vmcnt(18)
	v_fmac_f32_dpp v8, v240, v80 row_newbcast:6 row_mask:0xf bank_mask:0xf
	v_fmac_f32_dpp v9, v240, v81 row_newbcast:6 row_mask:0xf bank_mask:0xf
	v_fmac_f32_dpp v10, v240, v82 row_newbcast:6 row_mask:0xf bank_mask:0xf
	v_fmac_f32_dpp v11, v240, v83 row_newbcast:6 row_mask:0xf bank_mask:0xf
	v_fmac_f32_dpp v12, v240, v84 row_newbcast:6 row_mask:0xf bank_mask:0xf
	v_fmac_f32_dpp v13, v240, v85 row_newbcast:6 row_mask:0xf bank_mask:0xf
	v_fmac_f32_dpp v14, v240, v86 row_newbcast:6 row_mask:0xf bank_mask:0xf
	v_fmac_f32_dpp v15, v240, v87 row_newbcast:6 row_mask:0xf bank_mask:0xf
	s_waitcnt vmcnt(16)
	v_fmac_f32_dpp v8, v240, v88 row_newbcast:7 row_mask:0xf bank_mask:0xf
	v_fmac_f32_dpp v9, v240, v89 row_newbcast:7 row_mask:0xf bank_mask:0xf
	v_fmac_f32_dpp v10, v240, v90 row_newbcast:7 row_mask:0xf bank_mask:0xf
	v_fmac_f32_dpp v11, v240, v91 row_newbcast:7 row_mask:0xf bank_mask:0xf
	v_fmac_f32_dpp v12, v240, v92 row_newbcast:7 row_mask:0xf bank_mask:0xf
	v_fmac_f32_dpp v13, v240, v93 row_newbcast:7 row_mask:0xf bank_mask:0xf
	v_fmac_f32_dpp v14, v240, v94 row_newbcast:7 row_mask:0xf bank_mask:0xf
	v_fmac_f32_dpp v15, v240, v95 row_newbcast:7 row_mask:0xf bank_mask:0xf
	s_waitcnt vmcnt(14)
	v_fmac_f32_dpp v8, v240, v96 row_newbcast:8 row_mask:0xf bank_mask:0xf
	v_fmac_f32_dpp v9, v240, v97 row_newbcast:8 row_mask:0xf bank_mask:0xf
	v_fmac_f32_dpp v10, v240, v98 row_newbcast:8 row_mask:0xf bank_mask:0xf
	v_fmac_f32_dpp v11, v240, v99 row_newbcast:8 row_mask:0xf bank_mask:0xf
	v_fmac_f32_dpp v12, v240, v100 row_newbcast:8 row_mask:0xf bank_mask:0xf
	v_fmac_f32_dpp v13, v240, v101 row_newbcast:8 row_mask:0xf bank_mask:0xf
	v_fmac_f32_dpp v14, v240, v102 row_newbcast:8 row_mask:0xf bank_mask:0xf
	v_fmac_f32_dpp v15, v240, v103 row_newbcast:8 row_mask:0xf bank_mask:0xf
	s_waitcnt vmcnt(12)
	v_fmac_f32_dpp v8, v240, v104 row_newbcast:9 row_mask:0xf bank_mask:0xf
	v_fmac_f32_dpp v9, v240, v105 row_newbcast:9 row_mask:0xf bank_mask:0xf
	v_fmac_f32_dpp v10, v240, v106 row_newbcast:9 row_mask:0xf bank_mask:0xf
	v_fmac_f32_dpp v11, v240, v107 row_newbcast:9 row_mask:0xf bank_mask:0xf
	v_fmac_f32_dpp v12, v240, v108 row_newbcast:9 row_mask:0xf bank_mask:0xf
	v_fmac_f32_dpp v13, v240, v109 row_newbcast:9 row_mask:0xf bank_mask:0xf
	v_fmac_f32_dpp v14, v240, v110 row_newbcast:9 row_mask:0xf bank_mask:0xf
	v_fmac_f32_dpp v15, v240, v111 row_newbcast:9 row_mask:0xf bank_mask:0xf
	s_waitcnt vmcnt(10)
	v_fmac_f32_dpp v8, v240, v112 row_newbcast:10 row_mask:0xf bank_mask:0xf
	v_fmac_f32_dpp v9, v240, v113 row_newbcast:10 row_mask:0xf bank_mask:0xf
	v_fmac_f32_dpp v10, v240, v114 row_newbcast:10 row_mask:0xf bank_mask:0xf
	v_fmac_f32_dpp v11, v240, v115 row_newbcast:10 row_mask:0xf bank_mask:0xf
	v_fmac_f32_dpp v12, v240, v116 row_newbcast:10 row_mask:0xf bank_mask:0xf
	v_fmac_f32_dpp v13, v240, v117 row_newbcast:10 row_mask:0xf bank_mask:0xf
	v_fmac_f32_dpp v14, v240, v118 row_newbcast:10 row_mask:0xf bank_mask:0xf
	v_fmac_f32_dpp v15, v240, v119 row_newbcast:10 row_mask:0xf bank_mask:0xf
	s_waitcnt vmcnt(8)
	v_fmac_f32_dpp v8, v240, v120 row_newbcast:11 row_mask:0xf bank_mask:0xf
	v_fmac_f32_dpp v9, v240, v121 row_newbcast:11 row_mask:0xf bank_mask:0xf
	v_fmac_f32_dpp v10, v240, v122 row_newbcast:11 row_mask:0xf bank_mask:0xf
	v_fmac_f32_dpp v11, v240, v123 row_newbcast:11 row_mask:0xf bank_mask:0xf
	v_fmac_f32_dpp v12, v240, v124 row_newbcast:11 row_mask:0xf bank_mask:0xf
	v_fmac_f32_dpp v13, v240, v125 row_newbcast:11 row_mask:0xf bank_mask:0xf
	v_fmac_f32_dpp v14, v240, v126 row_newbcast:11 row_mask:0xf bank_mask:0xf
	v_fmac_f32_dpp v15, v240, v127 row_newbcast:11 row_mask:0xf bank_mask:0xf
	s_waitcnt vmcnt(6)
	v_fmac_f32_dpp v8, v240, v128 row_newbcast:12 row_mask:0xf bank_mask:0xf
	v_fmac_f32_dpp v9, v240, v129 row_newbcast:12 row_mask:0xf bank_mask:0xf
	v_fmac_f32_dpp v10, v240, v130 row_newbcast:12 row_mask:0xf bank_mask:0xf
	v_fmac_f32_dpp v11, v240, v131 row_newbcast:12 row_mask:0xf bank_mask:0xf
	v_fmac_f32_dpp v12, v240, v132 row_newbcast:12 row_mask:0xf bank_mask:0xf
	v_fmac_f32_dpp v13, v240, v133 row_newbcast:12 row_mask:0xf bank_mask:0xf
	v_fmac_f32_dpp v14, v240, v134 row_newbcast:12 row_mask:0xf bank_mask:0xf
	v_fmac_f32_dpp v15, v240, v135 row_newbcast:12 row_mask:0xf bank_mask:0xf
	s_waitcnt vmcnt(4)
	v_fmac_f32_dpp v8, v240, v136 row_newbcast:13 row_mask:0xf bank_mask:0xf
	v_fmac_f32_dpp v9, v240, v137 row_newbcast:13 row_mask:0xf bank_mask:0xf
	v_fmac_f32_dpp v10, v240, v138 row_newbcast:13 row_mask:0xf bank_mask:0xf
	v_fmac_f32_dpp v11, v240, v139 row_newbcast:13 row_mask:0xf bank_mask:0xf
	v_fmac_f32_dpp v12, v240, v140 row_newbcast:13 row_mask:0xf bank_mask:0xf
	v_fmac_f32_dpp v13, v240, v141 row_newbcast:13 row_mask:0xf bank_mask:0xf
	v_fmac_f32_dpp v14, v240, v142 row_newbcast:13 row_mask:0xf bank_mask:0xf
	v_fmac_f32_dpp v15, v240, v143 row_newbcast:13 row_mask:0xf bank_mask:0xf
	s_waitcnt vmcnt(2)
	v_fmac_f32_dpp v8, v240, v144 row_newbcast:14 row_mask:0xf bank_mask:0xf
	v_fmac_f32_dpp v9, v240, v145 row_newbcast:14 row_mask:0xf bank_mask:0xf
	v_fmac_f32_dpp v10, v240, v146 row_newbcast:14 row_mask:0xf bank_mask:0xf
	v_fmac_f32_dpp v11, v240, v147 row_newbcast:14 row_mask:0xf bank_mask:0xf
	v_fmac_f32_dpp v12, v240, v148 row_newbcast:14 row_mask:0xf bank_mask:0xf
	v_fmac_f32_dpp v13, v240, v149 row_newbcast:14 row_mask:0xf bank_mask:0xf
	v_fmac_f32_dpp v14, v240, v150 row_newbcast:14 row_mask:0xf bank_mask:0xf
	v_fmac_f32_dpp v15, v240, v151 row_newbcast:14 row_mask:0xf bank_mask:0xf
	s_waitcnt vmcnt(0)
	v_fmac_f32_dpp v8, v240, v152 row_newbcast:15 row_mask:0xf bank_mask:0xf
	v_fmac_f32_dpp v9, v240, v153 row_newbcast:15 row_mask:0xf bank_mask:0xf
	v_fmac_f32_dpp v10, v240, v154 row_newbcast:15 row_mask:0xf bank_mask:0xf
	v_fmac_f32_dpp v11, v240, v155 row_newbcast:15 row_mask:0xf bank_mask:0xf
	v_fmac_f32_dpp v12, v240, v156 row_newbcast:15 row_mask:0xf bank_mask:0xf
	v_fmac_f32_dpp v13, v240, v157 row_newbcast:15 row_mask:0xf bank_mask:0xf
	v_fmac_f32_dpp v14, v240, v158 row_newbcast:15 row_mask:0xf bank_mask:0xf
	v_fmac_f32_dpp v15, v240, v159 row_newbcast:15 row_mask:0xf bank_mask:0xf
	ds_bpermute_b32 v160, v238, v8
	ds_bpermute_b32 v161, v238, v9
	ds_bpermute_b32 v162, v238, v10
	ds_bpermute_b32 v163, v238, v11
	ds_bpermute_b32 v164, v238, v12
	ds_bpermute_b32 v165, v238, v13
	ds_bpermute_b32 v166, v238, v14
	ds_bpermute_b32 v167, v238, v15
	s_waitcnt lgkmcnt(0)
	v_add_f32_e32 v8, v8, v160
	v_add_f32_e32 v9, v9, v161
	v_add_f32_e32 v10, v10, v162
	v_add_f32_e32 v11, v11, v163
	v_add_f32_e32 v12, v12, v164
	v_add_f32_e32 v13, v13, v165
	v_add_f32_e32 v14, v14, v166
	v_add_f32_e32 v15, v15, v167
	ds_bpermute_b32 v160, v239, v8
	ds_bpermute_b32 v161, v239, v9
	ds_bpermute_b32 v162, v239, v10
	ds_bpermute_b32 v163, v239, v11
	ds_bpermute_b32 v164, v239, v12
	ds_bpermute_b32 v165, v239, v13
	ds_bpermute_b32 v166, v239, v14
	ds_bpermute_b32 v167, v239, v15
	s_waitcnt lgkmcnt(0)
	v_add_f32_e32 v8, v8, v160
	v_add_f32_e32 v9, v9, v161
	v_add_f32_e32 v10, v10, v162
	v_add_f32_e32 v11, v11, v163
	v_add_f32_e32 v12, v12, v164
	v_add_f32_e32 v13, v13, v165
	v_add_f32_e32 v14, v14, v166
	v_add_f32_e32 v15, v15, v167
	v_lshl_or_b32 v176, v20, 4, v18
	v_mul_u32_u24_e32 v176, 48, v176
	v_cmp_gt_u32_e32 vcc, 16, v18
	v_cmp_eq_u32_e64 s[6:7], 1, v21
	s_and_b64 s[6:7], s[6:7], vcc
	s_and_saveexec_b64 s[6:7], s[6:7]
	v_mov_b32_e32 v160, v16
	v_mov_b32_e32 v161, v17
	v_mov_b32_e32 v162, v8
	v_mov_b32_e32 v163, v9
	ds_write_b128 v176, v[160:163] offset:4096
	ds_write_b128 v176, v[10:13] offset:4112
	ds_write_b64 v176, v[14:15] offset:4128
	s_or_b64 exec, exec, s[6:7]
	s_waitcnt lgkmcnt(0)
	s_barrier
	v_cmp_gt_u32_e32 vcc, 16, v18
	v_cmp_eq_u32_e64 s[6:7], 0, v21
	s_and_b64 s[6:7], s[6:7], vcc
	s_and_saveexec_b64 s[6:7], s[6:7]
	s_cbranch_execz .Lsm0_mdone1
	global_load_dwordx4 v[172:175], v[244:245], off
	ds_read_b128 v[160:163], v176 offset:4096
	ds_read_b128 v[164:167], v176 offset:4112
	ds_read_b64 v[168:169], v176 offset:4128
	s_waitcnt lgkmcnt(0)
	v_max_f32_e32 v230, v16, v160
	v_sub_f32_e32 v231, v16, v230
	v_sub_f32_e32 v232, v160, v230
	v_mul_f32_e32 v231, 0x3fb8aa3b, v231
	v_mul_f32_e32 v232, 0x3fb8aa3b, v232
	v_exp_f32_e32 v231, v231
	v_exp_f32_e32 v232, v232
	s_nop 0
	v_mul_f32_e32 v233, v232, v161
	v_fmac_f32_e32 v233, v231, v17
	v_div_scale_f32 v234, s[8:9], v233, v233, 1.0
	v_rcp_f32_e32 v235, v234
	s_nop 0
	v_fma_f32 v236, -v234, v235, 1.0
	v_fmac_f32_e32 v235, v236, v235
	v_div_scale_f32 v236, vcc, 1.0, v233, 1.0
	v_mul_f32_e32 v237, v236, v235
	v_fma_f32 v176, -v234, v237, v236
	v_fmac_f32_e32 v237, v176, v235
	v_fma_f32 v234, -v234, v237, v236
	s_nop 0
	v_div_fmas_f32 v234, v234, v235, v237
	v_div_fixup_f32 v233, v234, v233, 1.0
	v_mul_f32_e32 v162, v232, v162
	v_fmac_f32_e32 v162, v231, v8
	v_mul_f32_e32 v162, v162, v233
	v_mul_f32_e32 v163, v232, v163
	v_fmac_f32_e32 v163, v231, v9
	v_mul_f32_e32 v163, v163, v233
	v_mul_f32_e32 v164, v232, v164
	v_fmac_f32_e32 v164, v231, v10
	v_mul_f32_e32 v164, v164, v233
	v_mul_f32_e32 v165, v232, v165
	v_fmac_f32_e32 v165, v231, v11
	v_mul_f32_e32 v165, v165, v233
	v_mul_f32_e32 v166, v232, v166
	v_fmac_f32_e32 v166, v231, v12
	v_mul_f32_e32 v166, v166, v233
	v_mul_f32_e32 v167, v232, v167
	v_fmac_f32_e32 v167, v231, v13
	v_mul_f32_e32 v167, v167, v233
	v_mul_f32_e32 v168, v232, v168
	v_fmac_f32_e32 v168, v231, v14
	v_mul_f32_e32 v168, v168, v233
	v_mul_f32_e32 v169, v232, v169
	v_fmac_f32_e32 v169, v231, v15
	v_mul_f32_e32 v169, v169, v233
	s_waitcnt vmcnt(0)
	v_lshlrev_b32_e32 v230, 16, v172
	v_and_b32_e32 v231, 0xffff0000, v172
	v_mul_f32_e32 v236, 0xbfb8aa3b, v230
	v_mul_f32_e32 v237, 0xbfb8aa3b, v231
	v_exp_f32_e32 v236, v236
	v_exp_f32_e32 v237, v237
	s_nop 0
	v_add_f32_e32 v236, 1.0, v236
	v_add_f32_e32 v237, 1.0, v237
	v_rcp_f32_e32 v236, v236
	v_rcp_f32_e32 v237, v237
	s_nop 0
	v_mul_f32_e32 v230, v230, v236
	v_mul_f32_e32 v231, v231, v237
	v_mul_f32_e32 v162, v162, v230
	v_mul_f32_e32 v163, v163, v231
	v_cvt_pk_bf16_f32 v172, v162, v163
	v_lshlrev_b32_e32 v230, 16, v173
	v_and_b32_e32 v231, 0xffff0000, v173
	v_mul_f32_e32 v236, 0xbfb8aa3b, v230
	v_mul_f32_e32 v237, 0xbfb8aa3b, v231
	v_exp_f32_e32 v236, v236
	v_exp_f32_e32 v237, v237
	s_nop 0
	v_add_f32_e32 v236, 1.0, v236
	v_add_f32_e32 v237, 1.0, v237
	v_rcp_f32_e32 v236, v236
	v_rcp_f32_e32 v237, v237
	s_nop 0
	v_mul_f32_e32 v230, v230, v236
	v_mul_f32_e32 v231, v231, v237
	v_mul_f32_e32 v164, v164, v230
	v_mul_f32_e32 v165, v165, v231
	v_cvt_pk_bf16_f32 v173, v164, v165
	v_lshlrev_b32_e32 v230, 16, v174
	v_and_b32_e32 v231, 0xffff0000, v174
	v_mul_f32_e32 v236, 0xbfb8aa3b, v230
	v_mul_f32_e32 v237, 0xbfb8aa3b, v231
	v_exp_f32_e32 v236, v236
	v_exp_f32_e32 v237, v237
	s_nop 0
	v_add_f32_e32 v236, 1.0, v236
	v_add_f32_e32 v237, 1.0, v237
	v_rcp_f32_e32 v236, v236
	v_rcp_f32_e32 v237, v237
	s_nop 0
	v_mul_f32_e32 v230, v230, v236
	v_mul_f32_e32 v231, v231, v237
	v_mul_f32_e32 v166, v166, v230
	v_mul_f32_e32 v167, v167, v231
	v_cvt_pk_bf16_f32 v174, v166, v167
	v_lshlrev_b32_e32 v230, 16, v175
	v_and_b32_e32 v231, 0xffff0000, v175
	v_mul_f32_e32 v236, 0xbfb8aa3b, v230
	v_mul_f32_e32 v237, 0xbfb8aa3b, v231
	v_exp_f32_e32 v236, v236
	v_exp_f32_e32 v237, v237
	s_nop 0
	v_add_f32_e32 v236, 1.0, v236
	v_add_f32_e32 v237, 1.0, v237
	v_rcp_f32_e32 v236, v236
	v_rcp_f32_e32 v237, v237
	s_nop 0
	v_mul_f32_e32 v230, v230, v236
	v_mul_f32_e32 v231, v231, v237
	v_mul_f32_e32 v168, v168, v230
	v_mul_f32_e32 v169, v169, v231
	v_cvt_pk_bf16_f32 v175, v168, v169
	global_store_dwordx4 v[246:247], v[172:175], off
